# L0 norm1 loop: all modulation chunks requested before the next-row prefetch; waits no longer sit behind the prefetch (true two-rows-in-flight)
# speedup vs baseline: 1.0212x; 1.0024x over previous
; __device__ __forceinline__ unsigned pk2(float lo, float hi) { return f2bf(lo) | (f2bf(hi) << 16); }
; __device__ __forceinline__ void norm_mod_phase(const float* lat, long lat_bs, const float* cx, long ctx_bs, const float* modl, int shoff, int scoff, bf16* XN, int skip_ctx, int gw, int NGW, float* xcopy, const float* part, int nkc, const float* pgate) {
;     ...
;     for (int row = gw; row < MROWS; row += NGW) {
;         const int s = sn; f32x4 v[4]; float ss = 0.f;
; #pragma unroll
;         for (int j = 0; j < 4; ++j) v[j] = vn[j];
;         if (row + NGW < MROWS) { const float* srcn = row_src(row + NGW, lat, lat_bs, cx, ctx_bs, sn); const f32x4* xr = (const f32x4*)srcn + lane;
; #pragma unroll
;             for (int j = 0; j < 4; ++j) vn[j] = xr[64 * j]; }
;     ...
;         const f32x4* sh = (const f32x4*)(modl + s * NMOD6 + shoff) + lane; const f32x4* sc = (const f32x4*)(modl + s * NMOD6 + scoff) + lane;
;         v2u* o8 = (v2u*)(XN + (size_t)row * DMODEL) + lane;
; #pragma unroll
;         for (int j = 0; j < 4; ++j) { const f32x4 a = sh[64 * j], m = sc[64 * j]; const f32x4 y = v[j] * rstd * (m + 1.0f) + a; v2u w; w.x = pk2(y.x, y.y); w.y = pk2(y.z, y.w); o8[64 * j] = w; }
.LBB0_113:
	s_lshl_b64 s[100:101], s[52:53], 12
	s_add_u32 s100, s50, s100
	s_addc_u32 s101, s51, s101
.LBB0_114:
	v_pk_mul_f32 v[44:45], v[14:15], v[14:15]
	v_pk_mul_f32 v[46:47], v[12:13], v[12:13]
	s_mulk_i32 s4, 0x1800
	v_mov_b32_e32 v48, v46
	v_mov_b32_e32 v49, v45
	v_pk_mov_b32 v[44:45], v[46:47], v[44:45] op_sel:[1,0]
	s_ashr_i32 s5, s4, 31
	v_pk_add_f32 v[44:45], v[44:45], v[48:49]
	s_lshl_b64 s[4:5], s[4:5], 2
	v_pk_add_f32 v[52:53], v[44:45], v[44:45] op_sel_hi:[0,1]
	v_pk_mul_f32 v[44:45], v[10:11], v[10:11]
	v_pk_mul_f32 v[46:47], v[8:9], v[8:9]
	s_add_u32 s48, s68, s4
	v_mov_b32_e32 v48, v46
	v_mov_b32_e32 v49, v45
	v_pk_mov_b32 v[44:45], v[46:47], v[44:45] op_sel:[1,0]
	s_addc_u32 s49, s69, s5
	v_pk_add_f32 v[44:45], v[44:45], v[48:49]
	v_lshl_add_u64 v[60:61], s[48:49], 0, v[32:33]
	v_pk_add_f32 v[54:55], v[44:45], v[44:45] op_sel_hi:[0,1]
	v_mul_f32_e32 v44, v4, v4
	v_add_co_u32_e32 v48, vcc, s1, v60
	v_pk_fma_f32 v[56:57], v[4:5], v[4:5], v[44:45] op_sel_hi:[1,1,0]
	v_mul_f32_e32 v44, v6, v6
	v_addc_co_u32_e32 v49, vcc, 0, v61, vcc
	v_pk_fma_f32 v[58:59], v[6:7], v[6:7], v[44:45] op_sel_hi:[1,1,0]
	global_load_dwordx4 v[44:47], v32, s[48:49]
	global_load_dwordx4 v[116:119], v[48:49], off offset:1024
	global_load_dwordx4 v[120:123], v32, s[48:49] offset:1024
	global_load_dwordx4 v[100:103], v[48:49], off offset:2048
	global_load_dwordx4 v[104:107], v32, s[48:49] offset:2048
	global_load_dwordx4 v[108:111], v[48:49], off offset:3072
	global_load_dwordx4 v[112:115], v32, s[48:49] offset:3072
	global_load_dwordx4 v[48:51], v[48:49], off
	s_and_b64 vcc, exec, s[46:47]
	s_cbranch_vccnz .Lnorm1_nopf
	global_load_dwordx4 v[16:19], v32, s[100:101]
	global_load_dwordx4 v[20:23], v32, s[100:101] offset:1024
	global_load_dwordx4 v[24:27], v32, s[100:101] offset:2048
	global_load_dwordx4 v[28:31], v32, s[100:101] offset:3072
	s_waitcnt vmcnt(4)
	s_branch .Lnorm1_join

; __device__ __forceinline__ unsigned pk2(float lo, float hi) { return f2bf(lo) | (f2bf(hi) << 16); }
; __device__ __forceinline__ void norm_mod_phase(const float* lat, long lat_bs, const float* cx, long ctx_bs, const float* modl, int shoff, int scoff, bf16* XN, int skip_ctx, int gw, int NGW, float* xcopy, const float* part, int nkc, const float* pgate) {
;     ...
;         for (int j = 0; j < 4; ++j) ss += (v[j].x * v[j].x + v[j].y * v[j].y) + (v[j].z * v[j].z + v[j].w * v[j].w);
;         if (xcopy && s == 4) {
;             const int b_ = row / TPB, cr = b_ * CTXL + (row - b_ * TPB); const f32x4* gp = (const f32x4*)(pgate + 4 * NMOD6) + lane;
;             f32x4 sm[4];
; #pragma unroll
;             for (int j = 0; j < 4; ++j) sm[j] = (f32x4){0.f, 0.f, 0.f, 0.f};
;             for (int kc = 0; kc < nkc; ++kc) { const f32x4* pp = (const f32x4*)(part + ((size_t)kc * 1024 + cr) * DMODEL) + lane;
; #pragma unroll
;                 for (int j = 0; j < 4; ++j) sm[j] += pp[64 * j]; }
;             f32x4* xc = (f32x4*)(xcopy + (size_t)row * DMODEL) + lane; ss = 0.f;
; #pragma unroll
;             for (int j = 0; j < 4; ++j) { v[j] += gp[64 * j] * sm[j]; xc[64 * j] = v[j]; ss += (v[j].x * v[j].x + v[j].y * v[j].y) + (v[j].z * v[j].z + v[j].w * v[j].w); } }
;         const float rstd = 1.0f / sqrtf(wave_sum(ss) * (1.0f / DMODEL) + EPS);
;         const f32x4* sh = (const f32x4*)(modl + s * NMOD6 + shoff) + lane; const f32x4* sc = (const f32x4*)(modl + s * NMOD6 + scoff) + lane;
;         v2u* o8 = (v2u*)(XN + (size_t)row * DMODEL) + lane;
; #pragma unroll
;         for (int j = 0; j < 4; ++j) { const f32x4 a = sh[64 * j], m = sc[64 * j]; const f32x4 y = v[j] * rstd * (m + 1.0f) + a; v2u w; w.x = pk2(y.x, y.y); w.y = pk2(y.z, y.w); o8[64 * j] = w; }
.Lnorm1_join:
	v_mul_f32_e32 v56, v0, v0
	v_mul_f32_e32 v58, v1, v1
	v_mul_f32_e32 v54, v2, v2
	v_mul_f32_e32 v52, v3, v3
	v_pk_add_f32 v[56:57], v[56:57], v[58:59]
	v_pk_add_f32 v[52:53], v[54:55], v[52:53]
	v_pk_add_f32 v[48:49], v[48:49], 1.0 op_sel_hi:[1,0]
	v_pk_add_f32 v[52:53], v[56:57], v[52:53]
	v_pk_add_f32 v[50:51], v[50:51], 1.0 op_sel_hi:[1,0]
	v_add_f32_e32 v52, v52, v53
	ds_bpermute_b32 v53, v38, v52
	s_waitcnt lgkmcnt(0)
	v_add_f32_e32 v52, v52, v53
	ds_bpermute_b32 v53, v39, v52
	s_waitcnt lgkmcnt(0)
	v_add_f32_e32 v52, v52, v53
	ds_bpermute_b32 v53, v40, v52
	s_waitcnt lgkmcnt(0)
	v_add_f32_e32 v52, v52, v53
	ds_bpermute_b32 v53, v41, v52
	s_waitcnt lgkmcnt(0)
	v_add_f32_e32 v52, v52, v53
	ds_bpermute_b32 v53, v42, v52
	s_waitcnt lgkmcnt(0)
	v_add_f32_e32 v52, v52, v53
	ds_bpermute_b32 v53, v43, v52
	s_waitcnt lgkmcnt(0)
	v_add_f32_e32 v52, v52, v53
	v_fmamk_f32 v52, v52, 0x3a800000, v36
	v_mul_f32_e32 v53, 0x4f800000, v52
	v_cmp_gt_f32_e32 vcc, s0, v52
	s_nop 1
	v_cndmask_b32_e32 v52, v52, v53, vcc
	v_sqrt_f32_e32 v53, v52
	s_nop 0
	v_add_u32_e32 v54, -1, v53
	v_add_u32_e32 v55, 1, v53
	v_fma_f32 v56, -v54, v53, v52
	v_fma_f32 v57, -v55, v53, v52
	v_cmp_ge_f32_e64 s[4:5], 0, v56
	s_nop 1
	v_cndmask_b32_e64 v53, v53, v54, s[4:5]
	v_cmp_lt_f32_e64 s[4:5], 0, v57
	s_nop 1
	v_cndmask_b32_e64 v53, v53, v55, s[4:5]
	v_mul_f32_e32 v54, 0x37800000, v53
	v_cndmask_b32_e32 v53, v53, v54, vcc
	v_cmp_class_f32_e32 vcc, v52, v37
	s_nop 1
	v_cndmask_b32_e32 v54, v53, v52, vcc
	v_div_scale_f32 v55, s[4:5], v54, v54, 1.0
	v_rcp_f32_e32 v56, v55
	v_div_scale_f32 v57, vcc, 1.0, v54, 1.0
	v_lshl_add_u64 v[52:53], v[60:61], 0, s[10:11]
	v_fma_f32 v58, -v55, v56, 1.0
	v_fmac_f32_e32 v56, v58, v56
	v_mul_f32_e32 v58, v57, v56
	v_fma_f32 v59, -v55, v58, v57
	v_fmac_f32_e32 v58, v59, v56
	v_fma_f32 v55, -v55, v58, v57
	v_div_fmas_f32 v55, v55, v56, v58
	v_div_fixup_f32 v54, v55, v54, 1.0
	v_pk_mul_f32 v[12:13], v[12:13], v[54:55] op_sel_hi:[1,0]
	v_pk_mul_f32 v[14:15], v[14:15], v[54:55] op_sel_hi:[1,0]
	v_pk_fma_f32 v[12:13], v[48:49], v[12:13], v[44:45]
	v_pk_fma_f32 v[14:15], v[50:51], v[14:15], v[46:47]
	v_bfe_u32 v44, v12, 16, 1
	v_bfe_u32 v45, v13, 16, 1
	v_add3_u32 v12, v12, v44, s3
	v_lshrrev_b32_e32 v12, 16, v12
	v_add3_u32 v13, v13, v45, s3
	v_and_or_b32 v12, v13, s14, v12
	v_bfe_u32 v13, v14, 16, 1
	v_add3_u32 v13, v14, v13, s3
	v_bfe_u32 v14, v15, 16, 1
	v_lshrrev_b32_e32 v13, 16, v13
	v_add3_u32 v14, v15, v14, s3
	v_and_or_b32 v13, v14, s14, v13
	global_store_dwordx2 v[34:35], v[12:13], off
	v_pk_mul_f32 v[8:9], v[8:9], v[54:55] op_sel_hi:[1,0]
	v_pk_mul_f32 v[10:11], v[10:11], v[54:55] op_sel_hi:[1,0]
	v_pk_mul_f32 v[4:5], v[4:5], v[54:55] op_sel_hi:[1,0]
	v_pk_mul_f32 v[6:7], v[6:7], v[54:55] op_sel_hi:[1,0]
	s_andn2_b64 vcc, exec, s[46:47]
	s_mov_b32 s4, s44
	v_pk_add_f32 v[14:15], v[118:119], 1.0 op_sel_hi:[1,0]
	v_pk_add_f32 v[12:13], v[116:117], 1.0 op_sel_hi:[1,0]
	v_pk_fma_f32 v[10:11], v[14:15], v[10:11], v[122:123]
	v_pk_fma_f32 v[8:9], v[12:13], v[8:9], v[120:121]
	v_bfe_u32 v14, v10, 16, 1
	v_bfe_u32 v12, v8, 16, 1
	v_bfe_u32 v13, v9, 16, 1
	v_bfe_u32 v15, v11, 16, 1
	v_add3_u32 v8, v8, v12, s3
	v_add3_u32 v10, v10, v14, s3
	v_add3_u32 v9, v9, v13, s3
	v_add3_u32 v11, v11, v15, s3
	v_lshrrev_b32_e32 v8, 16, v8
	v_lshrrev_b32_e32 v10, 16, v10
	v_and_or_b32 v8, v9, s14, v8
	v_and_or_b32 v9, v11, s14, v10
	global_store_dwordx2 v[34:35], v[8:9], off offset:512
	s_nop 0
	v_pk_add_f32 v[10:11], v[102:103], 1.0 op_sel_hi:[1,0]
	v_pk_add_f32 v[8:9], v[100:101], 1.0 op_sel_hi:[1,0]
	v_pk_fma_f32 v[6:7], v[6:7], v[10:11], v[106:107]
	v_pk_fma_f32 v[4:5], v[4:5], v[8:9], v[104:105]
	v_bfe_u32 v10, v6, 16, 1
	v_bfe_u32 v8, v4, 16, 1
	v_bfe_u32 v9, v5, 16, 1
	v_bfe_u32 v11, v7, 16, 1
	v_add3_u32 v4, v4, v8, s3
	v_add3_u32 v6, v6, v10, s3
	v_add3_u32 v5, v5, v9, s3
	v_add3_u32 v7, v7, v11, s3
	v_lshrrev_b32_e32 v4, 16, v4
	v_lshrrev_b32_e32 v6, 16, v6
	v_and_or_b32 v4, v5, s14, v4
	v_and_or_b32 v5, v7, s14, v6
	global_store_dwordx2 v[34:35], v[4:5], off offset:1024
	v_pk_mul_f32 v[52:53], v[0:1], v[54:55] op_sel_hi:[1,0]
	v_pk_mul_f32 v[54:55], v[2:3], v[54:55] op_sel_hi:[1,0]
	s_waitcnt vmcnt(3)
	v_mov_b64_e32 v[0:1], v[28:29]
	v_mov_b64_e32 v[4:5], v[24:25]
	v_mov_b64_e32 v[8:9], v[20:21]
	v_mov_b64_e32 v[12:13], v[16:17]
	v_mov_b64_e32 v[2:3], v[30:31]
	v_mov_b64_e32 v[6:7], v[26:27]
	v_mov_b64_e32 v[10:11], v[22:23]
	v_mov_b64_e32 v[14:15], v[18:19]
	v_pk_add_f32 v[46:47], v[110:111], 1.0 op_sel_hi:[1,0]
	v_pk_add_f32 v[44:45], v[108:109], 1.0 op_sel_hi:[1,0]
	v_pk_fma_f32 v[46:47], v[54:55], v[46:47], v[114:115]
	v_pk_fma_f32 v[44:45], v[52:53], v[44:45], v[112:113]
	v_bfe_u32 v50, v46, 16, 1
	v_bfe_u32 v48, v44, 16, 1
	v_bfe_u32 v49, v45, 16, 1
	v_bfe_u32 v51, v47, 16, 1
	v_add3_u32 v44, v44, v48, s3
	v_add3_u32 v46, v46, v50, s3
	v_add3_u32 v45, v45, v49, s3
	v_add3_u32 v47, v47, v51, s3
	v_lshrrev_b32_e32 v44, 16, v44
	v_lshrrev_b32_e32 v46, 16, v46
	v_and_or_b32 v44, v45, s14, v44
	v_and_or_b32 v45, v47, s14, v46
	global_store_dwordx2 v[34:35], v[44:45], off offset:1536
	v_lshl_add_u64 v[34:35], v[34:35], 0, s[12:13]
	s_cbranch_vccz .LBB0_120

; __global__ void __launch_bounds__(NTHREADS, 2) fwd_megakernel(Args a) {
;     __shared__ __attribute__((aligned(16))) unsigned char lds[LDS_TOTAL];
	.amdhsa_kernel _Z14fwd_megakernel4Args
		.amdhsa_group_segment_fixed_size 147456
		.amdhsa_private_segment_fixed_size 0
		.amdhsa_kernarg_size 448
		.amdhsa_user_sgpr_count 2
		.amdhsa_user_sgpr_dispatch_ptr 0
		.amdhsa_user_sgpr_queue_ptr 0
		.amdhsa_user_sgpr_kernarg_segment_ptr 1
		.amdhsa_user_sgpr_dispatch_id 0
		.amdhsa_user_sgpr_kernarg_preload_length 0
		.amdhsa_user_sgpr_kernarg_preload_offset 0
		.amdhsa_user_sgpr_private_segment_size 0
		.amdhsa_uses_dynamic_stack 0
		.amdhsa_enable_private_segment 0
		.amdhsa_system_sgpr_workgroup_id_x 1
		.amdhsa_system_sgpr_workgroup_id_y 0
		.amdhsa_system_sgpr_workgroup_id_z 0
		.amdhsa_system_sgpr_workgroup_info 0
		.amdhsa_system_vgpr_workitem_id 2
		.amdhsa_next_free_vgpr 255
		.amdhsa_next_free_sgpr 102
		.amdhsa_accum_offset 256
		.amdhsa_reserve_vcc 1
		.amdhsa_float_round_mode_32 0
		.amdhsa_float_round_mode_16_64 0
		.amdhsa_float_denorm_mode_32 3
		.amdhsa_float_denorm_mode_16_64 3
		.amdhsa_dx10_clamp 1
		.amdhsa_ieee_mode 1
		.amdhsa_fp16_overflow 0
		.amdhsa_tg_split 0
		.amdhsa_exception_fp_ieee_invalid_op 0
		.amdhsa_exception_fp_denorm_src 0
		.amdhsa_exception_fp_ieee_div_zero 0
		.amdhsa_exception_fp_ieee_overflow 0
		.amdhsa_exception_fp_ieee_underflow 0
		.amdhsa_exception_fp_ieee_inexact 0
		.amdhsa_exception_int_div_zero 0
	.end_amdhsa_kernel

; __global__ void __launch_bounds__(NTHREADS, 2) fwd_megakernel(Args a) {
;     __shared__ __attribute__((aligned(16))) unsigned char lds[LDS_TOTAL];
amdhsa.kernels:
  - .agpr_count:     0
    .args:
      - .offset:         0
        .size:           192
        .value_kind:     by_value
      - .offset:         192
        .size:           4
        .value_kind:     hidden_block_count_x
      - .offset:         196
        .size:           4
        .value_kind:     hidden_block_count_y
      - .offset:         200
        .size:           4
        .value_kind:     hidden_block_count_z
      - .offset:         204
        .size:           2
        .value_kind:     hidden_group_size_x
      - .offset:         206
        .size:           2
        .value_kind:     hidden_group_size_y
      - .offset:         208
        .size:           2
        .value_kind:     hidden_group_size_z
      - .offset:         210
        .size:           2
        .value_kind:     hidden_remainder_x
      - .offset:         212
        .size:           2
        .value_kind:     hidden_remainder_y
      - .offset:         214
        .size:           2
        .value_kind:     hidden_remainder_z
      - .offset:         232
        .size:           8
        .value_kind:     hidden_global_offset_x
      - .offset:         240
        .size:           8
        .value_kind:     hidden_global_offset_y
      - .offset:         248
        .size:           8
        .value_kind:     hidden_global_offset_z
      - .offset:         256
        .size:           2
        .value_kind:     hidden_grid_dims
      - .offset:         280
        .size:           8
        .value_kind:     hidden_multigrid_sync_arg
    .group_segment_fixed_size: 147456
    .kernarg_segment_align: 8
    .kernarg_segment_size: 448
    .language:       OpenCL C
    .language_version:
      - 2
      - 0
    .max_flat_workgroup_size: 512
    .name:           _Z14fwd_megakernel4Args
    .private_segment_fixed_size: 0
    .sgpr_count:     108
    .sgpr_spill_count: 32
    .symbol:         _Z14fwd_megakernel4Args.kd
    .uniform_work_group_size: 1
    .uses_dynamic_stack: false
    .vgpr_count:     255
    .vgpr_spill_count: 0
    .wavefront_size: 64
